# GEMM phase prologue: second K-tile staging loads issued before the first wait and barrier (14 loads in flight)
# baseline (speedup 1.0000x reference)
.LBB0_147:
	v_bfe_u32 v16, v0, 4, 2
	s_add_u32 s12, s12, 0xb200000
	v_and_b32_e32 v166, 15, v0
	v_lshlrev_b32_e32 v18, 4, v16
	v_lshlrev_b32_e32 v19, 2, v0
	s_addc_u32 s13, s13, 0
	s_and_b32 s18, s15, 3
	v_lshl_or_b32 v18, v166, 6, v18
	s_lshl_b32 s15, s16, 13
	v_and_b32_e32 v19, 32, v19
	s_add_i32 m0, s23, 0x18000
	v_lshl_add_u64 v[8:9], v[8:9], 0, s[98:99]
	s_lshl_b32 s51, s16, 6
	v_bitop3_b32 v20, v18, s15, v19 bitop3:0xde
	s_lshl_b32 s19, s18, 5
	s_lshl_b32 s15, s18, 12
	global_load_lds_dwordx4 v[8:9], off
	v_lshl_add_u64 v[6:7], v[6:7], 0, s[98:99]
	s_add_i32 m0, s23, 0x1a000
	s_add_i32 s52, s23, 0x8000
	s_add_i32 s53, s23, 0xa000
	global_load_lds_dwordx4 v[6:7], off
	v_lshl_add_u64 v[2:3], v[2:3], 0, s[98:99]
	s_mov_b32 m0, s52
	s_add_u32 s16, s26, 0x40080
	global_load_lds_dwordx4 v[2:3], off
	v_lshl_add_u64 v[2:3], v[4:5], 0, s[98:99]
	s_mov_b32 m0, s53
	s_addc_u32 s17, s27, 0
	global_load_lds_dwordx4 v[2:3], off
	s_add_i32 m0, s23, 0x1c000
	v_lshl_add_u64 v[2:3], s[16:17], 0, v[132:133]
	global_load_lds_dwordx4 v[2:3], off
	v_lshl_add_u64 v[2:3], s[16:17], 0, v[136:137]
	s_add_i32 m0, s23, 0x1e000
	v_and_b32_e32 v0, 16, v0
	global_load_lds_dwordx4 v[2:3], off
	s_waitcnt vmcnt(8)
	s_barrier
	v_cmp_eq_u32_e32 vcc, 0, v0
	v_lshlrev_b32_e32 v0, 14, v10
	v_and_b32_e32 v0, 0xffff8000, v0
	v_lshl_add_u32 v0, v11, 11, v0
	v_and_b32_e32 v2, 1, v10
	v_lshl_or_b32 v0, v2, 6, v0
	s_cmpk_lt_u32 s14, 0x100
	v_lshl_add_u32 v138, v12, 1, v0
	v_lshlrev_b32_e32 v0, 14, v13
	v_bitop3_b32 v167, v18, s15, v19 bitop3:0xde
	s_cselect_b64 s[14:15], -1, 0
	s_cmp_gt_u32 s18, 1
	v_and_b32_e32 v0, 0xffff8000, v0
	v_lshlrev_b32_e32 v17, 3, v16
	s_waitcnt vmcnt(6)
	s_cselect_b64 s[16:17], -1, 0
	s_add_i32 s20, s19, 0x440
	v_lshl_add_u32 v0, v14, 11, v0
	v_and_b32_e32 v2, 1, v13
	v_or_b32_e32 v169, s20, v17
	v_lshl_or_b32 v0, v2, 6, v0
	v_cmp_gt_u32_e64 s[38:39], 2, v16
	s_mov_b32 s54, 0
	v_cndmask_b32_e64 v168, v231, 1.0, vcc
	v_add_u32_e32 v170, 64, v169
	v_lshl_or_b32 v171, s18, 6, v17
	v_or_b32_e32 v172, s19, v17
	v_mov_b32_e32 v139, v1
	v_lshl_add_u32 v140, v15, 1, v0
	v_mov_b32_e32 v141, v1
	v_add_u32_e32 v173, 0, v20
	s_barrier
	s_branch .LBB0_150

.LBB0_202:
	s_lshl_b32 s16, s16, 5
	s_and_b32 s26, s16, 0x60
	s_lshl_b32 s13, s25, 13
	s_lshl_b32 s27, s26, 7
	s_and_b64 s[16:17], s[18:19], exec
	s_movk_i32 s16, 0x1400
	s_cselect_b32 s30, s16, 0x2000
	v_readlane_b32 s16, v248, 8
	v_readlane_b32 s17, v248, 9
	s_and_b64 s[16:17], s[16:17], exec
	s_cselect_b32 s31, 0x2d000, 0
	s_add_u32 s16, s20, 0x4c00000
	s_addc_u32 s17, s21, 0
	s_add_u32 s31, s20, s31
	s_addc_u32 s38, s21, 0
	s_and_b64 s[20:21], s[22:23], exec
	s_cselect_b32 s20, 0x800, s30
	s_lshl_b32 s20, s20, 2
	s_add_u32 s53, s31, s20
	s_addc_u32 s94, s38, 0
	s_add_i32 m0, s93, 0x18000
	v_lshl_add_u64 v[2:3], v[2:3], 0, s[98:99]
	global_load_lds_dwordx4 v[2:3], off
	v_lshl_add_u64 v[2:3], v[4:5], 0, s[98:99]
	s_add_i32 m0, s93, 0x1a000
	s_add_i32 s95, s93, 0x8000
	global_load_lds_dwordx4 v[2:3], off
	v_lshl_add_u64 v[2:3], v[10:11], 0, s[98:99]
	s_mov_b32 m0, s95
	s_add_i32 s54, s93, 0xa000
	global_load_lds_dwordx4 v[2:3], off
	v_lshl_add_u64 v[2:3], v[12:13], 0, s[98:99]
	s_mov_b32 m0, s54
	v_cndmask_b32_e64 v144, 0.5, 1.0, s[18:19]
	global_load_lds_dwordx4 v[2:3], off
	s_add_i32 m0, s93, 0x1c000
	v_lshl_add_u64 v[2:3], v[6:7], 0, s[98:99]
	global_load_lds_dwordx4 v[2:3], off
	v_lshl_add_u64 v[2:3], v[8:9], 0, s[98:99]
	s_add_i32 m0, s93, 0x1e000
	s_cmpk_lt_u32 s24, 0x100
	global_load_lds_dwordx4 v[2:3], off
	s_waitcnt vmcnt(8)
	s_barrier
	v_lshrrev_b32_e32 v3, 1, v14
	v_and_b32_e32 v3, 24, v3
	v_and_b32_e32 v2, 15, v14
	v_lshlrev_b32_e32 v4, 1, v3
	v_lshl_or_b32 v174, s25, 6, v2
	v_lshl_or_b32 v2, v2, 6, v4
	v_lshlrev_b32_e32 v4, 2, v14
	v_and_b32_e32 v4, 32, v4
	v_bitop3_b32 v5, v2, s13, v4 bitop3:0xde
	v_bitop3_b32 v175, v2, s27, v4 bitop3:0xde
	v_cvt_f32_ubyte0_e32 v2, s51
	v_rcp_iflag_f32_e32 v2, v2
	s_cselect_b64 s[18:19], -1, 0
	s_cmp_lg_u64 s[8:9], 0
	s_cselect_b64 s[20:21], -1, 0
	v_mul_f32_e32 v2, 0x4f7ffffe, v2
	v_cvt_u32_f32_e32 v2, v2
	v_or_b32_e32 v183, s26, v3
	s_sub_i32 s13, 0, s51
	v_mov_b32_e32 v3, v1
	v_readfirstlane_b32 s22, v2
	v_add_u32_e32 v2, v17, v15
	v_add_lshl_u32 v2, v2, v16, 1
	s_waitcnt vmcnt(6)
	s_mul_i32 s13, s13, s22
	v_lshl_add_u64 v[148:149], s[96:97], 0, v[2:3]
	v_add_u32_e32 v2, v20, v18
	s_mul_hi_u32 s13, s22, s13
	v_add_lshl_u32 v2, v2, v19, 1
	s_mov_b32 s55, 0
	v_mov_b32_e32 v146, v144
	v_mov_b32_e32 v147, v144
	v_or_b32_e32 v176, 16, v174
	v_or_b32_e32 v177, 32, v174
	v_or_b32_e32 v178, 48, v174
	v_add_u32_e32 v179, 0x80, v174
	v_add_u32_e32 v180, 0x90, v174
	v_add_u32_e32 v181, 0xa0, v174
	v_add_u32_e32 v182, 0xb0, v174
	s_add_i32 s56, s22, s13
	v_lshl_add_u64 v[150:151], s[96:97], 0, v[2:3]
	v_add_u32_e32 v184, 0, v5
	s_xor_b64 s[20:21], s[20:21], -1
	s_barrier
	s_branch .LBB0_205

.LBB0_365:
	s_add_u32 s6, s6, 0xb200000
	s_addc_u32 s7, s7, 0
	s_lshl_b32 s14, s14, 5
	s_and_b32 s17, s14, 0x60
	s_add_i32 m0, s27, 0x18000
	v_lshl_add_u64 v[8:9], v[8:9], 0, s[98:99]
	s_lshl_b32 s16, s13, 13
	s_lshl_b32 s18, s17, 7
	global_load_lds_dwordx4 v[8:9], off
	v_lshl_add_u64 v[6:7], v[6:7], 0, s[98:99]
	s_add_i32 m0, s27, 0x1a000
	s_add_i32 s49, s27, 0x8000
	s_add_i32 s51, s27, 0xa000
	global_load_lds_dwordx4 v[6:7], off
	v_lshl_add_u64 v[2:3], v[2:3], 0, s[98:99]
	s_mov_b32 m0, s49
	s_add_u32 s14, s30, 0x40080
	global_load_lds_dwordx4 v[2:3], off
	v_lshl_add_u64 v[2:3], v[4:5], 0, s[98:99]
	s_mov_b32 m0, s51
	s_addc_u32 s15, s31, 0
	global_load_lds_dwordx4 v[2:3], off
	s_add_i32 m0, s27, 0x1c000
	v_lshl_add_u64 v[2:3], s[14:15], 0, v[0:1]
	global_load_lds_dwordx4 v[2:3], off
	v_lshl_add_u64 v[2:3], s[14:15], 0, v[134:135]
	s_add_i32 m0, s27, 0x1e000
	s_cmpk_lt_u32 s12, 0x100
	global_load_lds_dwordx4 v[2:3], off
	s_waitcnt vmcnt(8)
	s_barrier
	v_lshrrev_b32_e32 v3, 1, v10
	v_and_b32_e32 v3, 24, v3
	v_and_b32_e32 v2, 15, v10
	v_lshlrev_b32_e32 v4, 1, v3
	v_lshl_or_b32 v144, s13, 6, v2
	v_lshl_or_b32 v2, v2, 6, v4
	v_lshlrev_b32_e32 v4, 2, v10
	v_and_b32_e32 v4, 32, v4
	v_bitop3_b32 v5, v2, s16, v4 bitop3:0xde
	v_bitop3_b32 v145, v2, s18, v4 bitop3:0xde
	v_lshlrev_b32_e32 v2, 14, v11
	v_and_b32_e32 v2, 0xffff8000, v2
	v_or_b32_e32 v146, s17, v3
	v_lshl_add_u32 v2, v12, 11, v2
	v_and_b32_e32 v3, 1, v11
	v_lshl_or_b32 v2, v3, 6, v2
	v_lshl_add_u32 v136, v13, 1, v2
	v_lshlrev_b32_e32 v2, 14, v14
	v_and_b32_e32 v2, 0xffff8000, v2
	s_waitcnt vmcnt(6)
	v_lshl_add_u32 v2, v15, 11, v2
	v_and_b32_e32 v3, 1, v14
	v_lshl_or_b32 v2, v3, 6, v2
	s_cselect_b64 s[12:13], -1, 0
	v_mov_b32_e32 v137, v1
	v_lshl_add_u32 v138, v16, 1, v2
	v_mov_b32_e32 v139, v1
	s_mov_b32 s52, 0
	v_add_u32_e32 v147, 0, v5
	s_barrier
	s_branch .LBB0_368
